# mixers A/B/D: cross-half row max by v_permlane32_swap instead of ds_bpermute; V-fragment wait moved to the first P.V MFMA
# speedup vs baseline: 1.0169x; 1.0073x over previous
; __device__ __forceinline__ float shx(float v, int mask, int lane) { return __builtin_bit_cast(float, __builtin_amdgcn_ds_bpermute((lane ^ mask) << 2, __builtin_bit_cast(int, v))); }
; template <class BiasF> ...
;     ...
;             for (int d0 = 0; d0 < 4; ++d0) sc = __builtin_amdgcn_mfma_f32_32x32x16_bf16(KF[d0], qr[d0], sc, 0, 0, 0);
;             const float ktf = (float)(kt + 8 * hi);
;             float tmax = -3.0e38f;
; #pragma unroll
;             for (int r = 0; r < 16; ++r) { sc[r] = sc[r] * c2 + bias.at(r32, kt, ktf + (float)(16 * (r >> 3) + 4 * ((r >> 2) & 1) + (r & 3)), r); tmax = fmaxf(tmax, sc[r]); }
;             tmax = fmaxf(tmax, shx(tmax, 32, lane));
;             if (__any(tmax > m)) { const float mn = fmaxf(m, tmax); const float alpha = __builtin_amdgcn_exp2f(m - mn); m = mn; l *= alpha;
; #pragma unroll
;                 for (int i2 = 0; i2 < 2; ++i2)
; #pragma unroll
;                     for (int r = 0; r < 16; ++r) o[i2][r] *= alpha; }
.LBB0_410:
	s_cmp_ge_u32 s29, s31
	v_cmp_lt_u32_e32 vcc, s29, v84
	s_cselect_b64 s[26:27], -1, 0
	s_or_b64 s[26:27], vcc, s[26:27]
	s_and_b64 vcc, exec, s[26:27]
	s_cbranch_vccnz .LBB0_414
	v_lshl_add_u32 v104, s30, 14, v81
	ds_read_b128 v[34:37], v104
	v_add_u32_e32 v38, s29, v68
	v_cvt_f32_i32_e32 v87, v38
	ds_read_b128 v[92:95], v104 offset:1024
	ds_read_b128 v[96:99], v104 offset:2048
	ds_read_b128 v[100:103], v104 offset:3072
	s_waitcnt lgkmcnt(0)
	v_mfma_f32_32x32x16_bf16 v[34:49], v[34:37], v[50:53], 0
	v_sub_f32_e32 v88, v85, v87
	v_add_f32_e32 v89, 1.0, v87
	v_add_f32_e32 v90, 2.0, v87
	v_mul_f32_e64 v105, v86, |v88|
	v_sub_f32_e32 v89, v85, v89
	v_cmp_le_f32_e64 vcc, |v88|, s19
	v_add_f32_e32 v91, 0x40400000, v87
	v_mfma_f32_32x32x16_bf16 v[34:49], v[92:95], v[54:57], v[34:49]
	v_sub_f32_e32 v106, v85, v90
	v_cndmask_b32_e32 v90, v203, v105, vcc
	v_mul_f32_e64 v88, v86, |v89|
	v_cmp_le_f32_e64 vcc, |v89|, s19
	v_sub_f32_e32 v107, v85, v91
	v_mul_f32_e64 v91, v86, |v106|
	v_cndmask_b32_e32 v92, v203, v88, vcc
	v_mfma_f32_32x32x16_bf16 v[34:49], v[96:99], v[58:61], v[34:49]
	v_cmp_le_f32_e64 vcc, |v106|, s19
	v_add_f32_e32 v89, 4.0, v87
	v_mul_f32_e64 v93, v86, |v107|
	v_cndmask_b32_e32 v91, v203, v91, vcc
	v_cmp_le_f32_e64 vcc, |v107|, s19
	v_sub_f32_e32 v89, v85, v89
	v_mfma_f32_32x32x16_bf16 v[34:49], v[100:103], v[62:65], v[34:49]
	v_cndmask_b32_e32 v88, v203, v93, vcc
	v_mul_f32_e64 v93, v86, |v89|
	v_cmp_le_f32_e64 vcc, |v89|, s19
	s_nop 1
	v_cndmask_b32_e32 v89, v203, v93, vcc
	v_add_f32_e32 v93, 0x40a00000, v87
	v_sub_f32_e32 v93, v85, v93
	s_nop 3
	v_fmac_f32_e32 v92, 0x3e38aa3b, v35
	v_add_f32_e32 v35, 0x40c00000, v87
	v_mul_f32_e64 v94, v86, |v93|
	v_cmp_le_f32_e64 vcc, |v93|, s19
	v_sub_f32_e32 v35, v85, v35
	v_fmac_f32_e32 v91, 0x3e38aa3b, v36
	v_cndmask_b32_e32 v93, v203, v94, vcc
	v_mul_f32_e64 v36, v86, |v35|
	v_cmp_le_f32_e64 vcc, |v35|, s19
	v_add_f32_e32 v35, 0x40e00000, v87
	v_sub_f32_e32 v35, v85, v35
	v_cndmask_b32_e32 v95, v203, v36, vcc
	v_mul_f32_e64 v36, v86, |v35|
	v_cmp_le_f32_e64 vcc, |v35|, s19
	v_add_f32_e32 v35, 0x41800000, v87
	v_sub_f32_e32 v35, v85, v35
	v_cndmask_b32_e32 v94, v203, v36, vcc
	v_mul_f32_e64 v36, v86, |v35|
	v_cmp_le_f32_e64 vcc, |v35|, s19
	v_add_f32_e32 v35, 0x41880000, v87
	v_sub_f32_e32 v35, v85, v35
	v_cndmask_b32_e32 v97, v203, v36, vcc
	v_mul_f32_e64 v36, v86, |v35|
	v_cmp_le_f32_e64 vcc, |v35|, s19
	v_add_f32_e32 v35, 0x41900000, v87
	v_sub_f32_e32 v35, v85, v35
	v_cndmask_b32_e32 v96, v203, v36, vcc
	v_mul_f32_e64 v36, v86, |v35|
	v_cmp_le_f32_e64 vcc, |v35|, s19
	v_add_f32_e32 v35, 0x41980000, v87
	v_sub_f32_e32 v35, v85, v35
	v_cndmask_b32_e32 v98, v203, v36, vcc
	v_mul_f32_e64 v36, v86, |v35|
	v_cmp_le_f32_e64 vcc, |v35|, s19
	v_add_f32_e32 v35, 0x41a00000, v87
	v_sub_f32_e32 v35, v85, v35
	v_cndmask_b32_e32 v99, v203, v36, vcc
	v_mul_f32_e64 v36, v86, |v35|
	v_cmp_le_f32_e64 vcc, |v35|, s19
	v_add_f32_e32 v35, 0x41a80000, v87
	v_fmac_f32_e32 v90, 0x3e38aa3b, v34
	v_sub_f32_e32 v35, v85, v35
	v_fmac_f32_e32 v88, 0x3e38aa3b, v37
	v_max3_f32 v34, v90, s53, v92
	v_cndmask_b32_e32 v100, v203, v36, vcc
	v_mul_f32_e64 v36, v86, |v35|
	v_cmp_le_f32_e64 vcc, |v35|, s19
	v_add_f32_e32 v35, 0x41b00000, v87
	v_fmac_f32_e32 v89, 0x3e38aa3b, v38
	v_max3_f32 v34, v34, v91, v88
	v_fmac_f32_e32 v93, 0x3e38aa3b, v39
	v_sub_f32_e32 v35, v85, v35
	v_max3_f32 v34, v34, v89, v93
	v_fmac_f32_e32 v95, 0x3e38aa3b, v40
	v_fmac_f32_e32 v94, 0x3e38aa3b, v41
	v_cndmask_b32_e32 v101, v203, v36, vcc
	v_mul_f32_e64 v36, v86, |v35|
	v_cmp_le_f32_e64 vcc, |v35|, s19
	v_add_f32_e32 v35, 0x41b80000, v87
	v_max3_f32 v34, v34, v95, v94
	v_fmac_f32_e32 v97, 0x3e38aa3b, v42
	v_fmac_f32_e32 v96, 0x3e38aa3b, v43
	v_sub_f32_e32 v35, v85, v35
	v_max3_f32 v34, v34, v97, v96
	v_fmac_f32_e32 v98, 0x3e38aa3b, v44
	v_fmac_f32_e32 v99, 0x3e38aa3b, v45
	v_cndmask_b32_e32 v102, v203, v36, vcc
	v_mul_f32_e64 v36, v86, |v35|
	v_cmp_le_f32_e64 vcc, |v35|, s19
	v_max3_f32 v34, v34, v98, v99
	v_fmac_f32_e32 v100, 0x3e38aa3b, v46
	v_fmac_f32_e32 v101, 0x3e38aa3b, v47
	v_cndmask_b32_e32 v87, v203, v36, vcc
	v_max3_f32 v34, v34, v100, v101
	v_fmac_f32_e32 v102, 0x3e38aa3b, v48
	v_fmac_f32_e32 v87, 0x3e38aa3b, v49
	v_max3_f32 v103, v34, v102, v87
	v_mov_b32_e32 v105, v103
	ds_read_b128 v[46:49], v104 offset:4096
	ds_read_b128 v[38:41], v104 offset:5120
	ds_read_b128 v[42:45], v104 offset:6144
	ds_read_b128 v[34:37], v104 offset:7168
	v_permlane32_swap_b32_e32 v105, v103
	v_max_f32_e32 v104, v105, v105
	v_max_f32_e32 v103, v103, v104
	v_cmp_gt_f32_e32 vcc, v103, v82
	s_cbranch_vccz .LBB0_413
	v_max_f32_e32 v103, v103, v103
	v_max_f32_e32 v104, v82, v82
	v_max_f32_e32 v103, v104, v103
	v_sub_f32_e32 v82, v82, v103
	v_exp_f32_e32 v82, v82
	s_nop 0
	v_pk_mul_f32 v[16:17], v[16:17], v[82:83] op_sel_hi:[1,0]
	v_pk_mul_f32 v[14:15], v[14:15], v[82:83] op_sel_hi:[1,0]
	v_pk_mul_f32 v[12:13], v[12:13], v[82:83] op_sel_hi:[1,0]
	v_pk_mul_f32 v[10:11], v[10:11], v[82:83] op_sel_hi:[1,0]
	v_pk_mul_f32 v[8:9], v[8:9], v[82:83] op_sel_hi:[1,0]
	v_pk_mul_f32 v[6:7], v[6:7], v[82:83] op_sel_hi:[1,0]
	v_pk_mul_f32 v[4:5], v[4:5], v[82:83] op_sel_hi:[1,0]
	v_pk_mul_f32 v[2:3], v[2:3], v[82:83] op_sel_hi:[1,0]
	v_pk_mul_f32 v[32:33], v[32:33], v[82:83] op_sel_hi:[1,0]
	v_pk_mul_f32 v[30:31], v[30:31], v[82:83] op_sel_hi:[1,0]
	v_pk_mul_f32 v[28:29], v[28:29], v[82:83] op_sel_hi:[1,0]
	v_pk_mul_f32 v[26:27], v[26:27], v[82:83] op_sel_hi:[1,0]
	v_pk_mul_f32 v[24:25], v[24:25], v[82:83] op_sel_hi:[1,0]
	v_pk_mul_f32 v[22:23], v[22:23], v[82:83] op_sel_hi:[1,0]
	v_pk_mul_f32 v[20:21], v[20:21], v[82:83] op_sel_hi:[1,0]
	v_pk_mul_f32 v[18:19], v[18:19], v[82:83] op_sel_hi:[1,0]
	v_mul_f32_e32 v83, v83, v82
	v_mov_b32_e32 v82, v103
; __device__ __forceinline__ unsigned cvtpk(float lo, float hi) { f32x2_t v = {lo, hi}; bf16x2_t b = __builtin_convertvector(v, bf16x2_t); return __builtin_bit_cast(unsigned, b); }
; template <class BiasF> ...
;     ...
;             float ps = 0.f;
; #pragma unroll
;             for (int r = 0; r < 16; ++r) { sc[r] = __builtin_amdgcn_exp2f(sc[r] - m); ps += sc[r]; asm volatile("" : "+v"(ps)); }
;             l += ps; u32x4 w0, w1;
;             w0.x = cvtpk(sc[0], sc[1]); w0.y = cvtpk(sc[2], sc[3]); w0.z = cvtpk(sc[4], sc[5]); w0.w = cvtpk(sc[6], sc[7]);
;             w1.x = cvtpk(sc[8], sc[9]); w1.y = cvtpk(sc[10], sc[11]); w1.z = cvtpk(sc[12], sc[13]); w1.w = cvtpk(sc[14], sc[15]);
;             const bf16x8 p0 = __builtin_bit_cast(bf16x8, w0), p1 = __builtin_bit_cast(bf16x8, w1);
; #pragma unroll
;             for (int i2 = 0; i2 < 2; ++i2) { o[i2] = __builtin_amdgcn_mfma_f32_32x32x16_bf16(VA[i2][0], p0, o[i2], 0, 0, 0); o[i2] = __builtin_amdgcn_mfma_f32_32x32x16_bf16(VA[i2][1], p1, o[i2], 0, 0, 0); }
.LBB0_413:
	v_sub_f32_e32 v90, v90, v82
	v_exp_f32_e32 v90, v90
	v_sub_f32_e32 v92, v92, v82
	v_exp_f32_e32 v92, v92
	v_sub_f32_e32 v91, v91, v82
	v_add_f32_e32 v103, 0, v90
	v_exp_f32_e32 v91, v91
	v_sub_f32_e32 v88, v88, v82
	v_exp_f32_e32 v104, v88
	v_add_f32_e32 v103, v103, v92
	v_sub_f32_e32 v88, v89, v82
	v_exp_f32_e32 v105, v88
	v_add_f32_e32 v103, v103, v91
	v_sub_f32_e32 v89, v93, v82
	v_exp_f32_e32 v93, v89
	v_add_f32_e32 v88, v104, v103
	v_sub_f32_e32 v89, v95, v82
	v_add_f32_e32 v88, v105, v88
	v_exp_f32_e32 v95, v89
	v_sub_f32_e32 v89, v94, v82
	v_add_f32_e32 v88, v93, v88
	v_exp_f32_e32 v94, v89
	v_sub_f32_e32 v89, v97, v82
	v_add_f32_e32 v88, v95, v88
	v_exp_f32_e32 v97, v89
	v_cvt_pk_bf16_f32 v89, v91, v104
	v_add_f32_e32 v88, v94, v88
	v_cvt_pk_bf16_f32 v91, v95, v94
	v_add_f32_e32 v103, v97, v88
	v_sub_f32_e32 v88, v96, v82
	v_exp_f32_e32 v96, v88
	v_sub_f32_e32 v88, v98, v82
	v_exp_f32_e32 v98, v88
	v_sub_f32_e32 v88, v99, v82
	v_exp_f32_e32 v99, v88
	v_sub_f32_e32 v88, v100, v82
	v_exp_f32_e32 v100, v88
	v_sub_f32_e32 v88, v101, v82
	v_exp_f32_e32 v101, v88
	v_cvt_pk_bf16_f32 v88, v90, v92
	v_cvt_pk_bf16_f32 v90, v105, v93
	v_sub_f32_e32 v102, v102, v82
	v_exp_f32_e32 v92, v102
	s_waitcnt lgkmcnt(0)
	v_mfma_f32_32x32x16_bf16 v[18:33], v[46:49], v[88:91], v[18:33]
	v_sub_f32_e32 v46, v87, v82
	v_exp_f32_e32 v87, v46
	v_cvt_pk_bf16_f32 v46, v97, v96
	v_cvt_pk_bf16_f32 v47, v98, v99
	v_cvt_pk_bf16_f32 v48, v100, v101
	v_cvt_pk_bf16_f32 v49, v92, v87
	v_mfma_f32_32x32x16_bf16 v[2:17], v[38:41], v[88:91], v[2:17]
	s_nop 0
	v_mfma_f32_32x32x16_bf16 v[18:33], v[42:45], v[46:49], v[18:33]
	v_add_f32_e32 v42, v96, v103
	s_nop 0
	v_add_f32_e32 v42, v98, v42
	s_nop 0
	v_add_f32_e32 v42, v99, v42
	v_mfma_f32_32x32x16_bf16 v[2:17], v[34:37], v[46:49], v[2:17]
	v_add_f32_e32 v42, v100, v42
	s_nop 0
	v_add_f32_e32 v38, v101, v42
	s_nop 0
	v_add_f32_e32 v38, v92, v38
	s_nop 0
	v_add_f32_e32 v38, v87, v38
	s_nop 0
	v_add_f32_e32 v83, v83, v38

; __device__ __forceinline__ float shx(float v, int mask, int lane) { return __builtin_bit_cast(float, __builtin_amdgcn_ds_bpermute((lane ^ mask) << 2, __builtin_bit_cast(int, v))); }
; template <class BiasF> ...
;     ...
;             for (int d0 = 0; d0 < 4; ++d0) sc = __builtin_amdgcn_mfma_f32_32x32x16_bf16(KF[d0], qr[d0], sc, 0, 0, 0);
;             const float ktf = (float)(kt + 8 * hi);
;             float tmax = -3.0e38f;
; #pragma unroll
;             for (int r = 0; r < 16; ++r) { sc[r] = sc[r] * c2 + bias.at(r32, kt, ktf + (float)(16 * (r >> 3) + 4 * ((r >> 2) & 1) + (r & 3)), r); tmax = fmaxf(tmax, sc[r]); }
;             tmax = fmaxf(tmax, shx(tmax, 32, lane));
;             if (__any(tmax > m)) { const float mn = fmaxf(m, tmax); const float alpha = __builtin_amdgcn_exp2f(m - mn); m = mn; l *= alpha;
; #pragma unroll
;                 for (int i2 = 0; i2 < 2; ++i2)
; #pragma unroll
;                     for (int r = 0; r < 16; ++r) o[i2][r] *= alpha; }
.LBB0_653:
	s_cmp_lt_i32 s31, s25
	s_cselect_b64 s[4:5], -1, 0
	s_cmp_ge_i32 s31, s29
	s_cselect_b64 s[38:39], -1, 0
	s_or_b64 s[4:5], s[4:5], s[38:39]
	s_and_b64 vcc, exec, s[4:5]
	s_cbranch_vccnz .LBB0_657
	v_lshl_add_u32 v108, s34, 13, v90
	ds_read_b128 v[34:37], v108
	ds_read_b128 v[92:95], v108 offset:1024
	ds_read_b128 v[96:99], v108 offset:2048
	ds_read_b128 v[100:103], v108 offset:3072
	s_add_i32 s4, s24, s36
	s_bitcmp0_b32 s36, 0
	s_cselect_b64 vcc, -1, 0
	s_lshr_b32 s4, s4, 1
	v_cndmask_b32_e32 v104, v82, v81, vcc
	s_sub_i32 s4, s4, s28
	v_cndmask_b32_e32 v111, v84, v83, vcc
	s_waitcnt lgkmcnt(0)
	v_mfma_f32_32x32x16_bf16 v[34:49], v[34:37], v[50:53], 0
	v_lshrrev_b32_e32 v107, 6, v104
	v_lshrrev_b32_e32 v109, 14, v104
	v_lshrrev_b32_e32 v110, 22, v104
	s_mulk_i32 s4, 0x7c
	v_and_b32_e32 v105, 31, v104
	v_and_b32_e32 v106, 0x80, v104
	s_add_i32 s36, s4, 0
	v_mfma_f32_32x32x16_bf16 v[34:49], v[92:95], v[54:57], v[34:49]
	v_and_b32_e32 v92, 0x7c, v107
	v_and_b32_e32 v93, 0x7c, v109
	v_and_b32_e32 v94, 0x7c, v110
	v_lshrrev_b32_e32 v107, 6, v111
	v_and_b32_e32 v95, 31, v111
	v_add_u32_e32 v92, s36, v92
	v_add_u32_e32 v93, s36, v93
	v_mfma_f32_32x32x16_bf16 v[34:49], v[96:99], v[58:61], v[34:49]
	v_lshrrev_b32_e32 v99, 22, v111
	v_lshrrev_b32_e32 v98, 14, v111
	v_and_b32_e32 v99, 0x7c, v99
	v_and_b32_e32 v96, 0x7c, v107
	v_lshl_add_u32 v97, v105, 2, s36
	v_add_u32_e32 v94, s36, v94
	v_and_b32_e32 v98, 0x7c, v98
	v_mfma_f32_32x32x16_bf16 v[34:49], v[100:103], v[62:65], v[34:49]
	v_add_u32_e32 v99, s36, v99
	v_cmp_eq_u32_e64 s[4:5], 0, v106
	v_lshl_add_u32 v95, v95, 2, s36
	v_add_u32_e32 v96, s36, v96
	v_add_u32_e32 v98, s36, v98
	ds_read_b32 v97, v97 offset:25444
	ds_read_b32 v92, v92 offset:25444
	ds_read_b32 v93, v93 offset:25444
	ds_read_b32 v94, v94 offset:25444
	ds_read_b32 v100, v95 offset:25444
	ds_read_b32 v101, v96 offset:25444
	ds_read_b32 v102, v98 offset:25444
	ds_read_b32 v103, v99 offset:25444
	s_waitcnt lgkmcnt(0)
	v_cndmask_b32_e64 v99, v203, v97, s[4:5]
	v_fmac_f32_e32 v99, 0x3e38aa3b, v34
	v_and_b32_e32 v34, 0x8000, v104
	v_cmp_eq_u32_e64 s[4:5], 0, v34
	s_nop 1
	v_cndmask_b32_e64 v97, v203, v92, s[4:5]
	v_fmac_f32_e32 v97, 0x3e38aa3b, v35
	v_and_b32_e32 v35, 0x800000, v104
	v_cmp_eq_u32_e64 s[4:5], 0, v35
	v_and_b32_e32 v35, 0x80, v111
	v_max3_f32 v34, v99, s53, v97
	v_cndmask_b32_e64 v98, v203, v93, s[4:5]
	v_cmp_lt_i32_e64 s[4:5], -1, v104
	v_fmac_f32_e32 v98, 0x3e38aa3b, v36
	s_nop 0
	v_cndmask_b32_e64 v95, v203, v94, s[4:5]
	v_cmp_eq_u32_e64 s[4:5], 0, v35
	v_and_b32_e32 v35, 0x8000, v111
	v_fmac_f32_e32 v95, 0x3e38aa3b, v37
	v_cndmask_b32_e64 v96, v203, v100, s[4:5]
	v_cmp_eq_u32_e64 s[4:5], 0, v35
	v_and_b32_e32 v35, 0x800000, v111
	v_fmac_f32_e32 v96, 0x3e38aa3b, v38
	v_cndmask_b32_e64 v93, v203, v101, s[4:5]
	v_cmp_eq_u32_e64 s[4:5], 0, v35
	v_cndmask_b32_e32 v35, v86, v85, vcc
	v_fmac_f32_e32 v93, 0x3e38aa3b, v39
	v_cndmask_b32_e64 v94, v203, v102, s[4:5]
	v_cmp_lt_i32_e64 s[4:5], -1, v111
	v_fmac_f32_e32 v94, 0x3e38aa3b, v40
	v_lshrrev_b32_e32 v38, 6, v35
	v_cndmask_b32_e64 v92, v203, v103, s[4:5]
	v_fmac_f32_e32 v92, 0x3e38aa3b, v41
	v_cndmask_b32_e32 v41, v88, v87, vcc
	v_lshrrev_b32_e32 v39, 14, v35
	v_lshrrev_b32_e32 v40, 22, v35
	v_lshrrev_b32_e32 v101, 6, v41
	v_lshrrev_b32_e32 v102, 14, v41
	v_and_b32_e32 v36, 31, v35
	v_and_b32_e32 v38, 0x7c, v38
	v_and_b32_e32 v39, 0x7c, v39
	v_and_b32_e32 v40, 0x7c, v40
	v_and_b32_e32 v100, 31, v41
	v_and_b32_e32 v101, 0x7c, v101
	v_and_b32_e32 v102, 0x7c, v102
	v_lshrrev_b32_e32 v103, 22, v41
	v_lshl_add_u32 v36, v36, 2, s36
	v_and_b32_e32 v37, 0x80, v35
	v_add_u32_e32 v38, s36, v38
	v_add_u32_e32 v39, s36, v39
	v_add_u32_e32 v40, s36, v40
	v_lshl_add_u32 v100, v100, 2, s36
	v_add_u32_e32 v101, s36, v101
	v_add_u32_e32 v102, s36, v102
	v_and_b32_e32 v103, 0x7c, v103
	v_add_u32_e32 v103, s36, v103
	ds_read_b32 v36, v36 offset:25444
	ds_read_b32 v38, v38 offset:25444
	ds_read_b32 v39, v39 offset:25444
	ds_read_b32 v40, v40 offset:25444
	ds_read_b32 v100, v100 offset:25444
	ds_read_b32 v101, v101 offset:25444
	ds_read_b32 v102, v102 offset:25444
	ds_read_b32 v109, v103 offset:25444
	v_cmp_eq_u32_e32 vcc, 0, v37
	v_max3_f32 v34, v34, v98, v95
	v_max3_f32 v34, v34, v96, v93
	s_waitcnt lgkmcnt(0)
	v_cndmask_b32_e32 v107, v203, v36, vcc
	v_and_b32_e32 v36, 0x8000, v35
	v_cmp_eq_u32_e32 vcc, 0, v36
	v_and_b32_e32 v36, 0x800000, v35
	v_max3_f32 v34, v34, v94, v92
	v_cndmask_b32_e32 v105, v203, v38, vcc
	v_cmp_eq_u32_e32 vcc, 0, v36
	v_fmac_f32_e32 v107, 0x3e38aa3b, v42
	v_fmac_f32_e32 v105, 0x3e38aa3b, v43
	v_cndmask_b32_e32 v106, v203, v39, vcc
	v_cmp_lt_i32_e32 vcc, -1, v35
	v_and_b32_e32 v35, 0x80, v41
	v_max3_f32 v34, v34, v107, v105
	v_cndmask_b32_e32 v103, v203, v40, vcc
	v_cmp_eq_u32_e32 vcc, 0, v35
	v_and_b32_e32 v35, 0x8000, v41
	v_fmac_f32_e32 v106, 0x3e38aa3b, v44
	v_cndmask_b32_e32 v104, v203, v100, vcc
	v_cmp_eq_u32_e32 vcc, 0, v35
	v_and_b32_e32 v35, 0x800000, v41
	v_fmac_f32_e32 v103, 0x3e38aa3b, v45
	v_cndmask_b32_e32 v101, v203, v101, vcc
	v_cmp_eq_u32_e32 vcc, 0, v35
	v_max3_f32 v34, v34, v106, v103
	v_fmac_f32_e32 v104, 0x3e38aa3b, v46
	v_cndmask_b32_e32 v102, v203, v102, vcc
	v_cmp_lt_i32_e32 vcc, -1, v41
	v_fmac_f32_e32 v101, 0x3e38aa3b, v47
	v_max3_f32 v34, v34, v104, v101
	v_cndmask_b32_e32 v100, v203, v109, vcc
	v_fmac_f32_e32 v102, 0x3e38aa3b, v48
	v_fmac_f32_e32 v100, 0x3e38aa3b, v49
	v_max3_f32 v109, v34, v102, v100
	v_mov_b32_e32 v110, v109
	ds_read_b128 v[46:49], v108 offset:4096
	ds_read_b128 v[38:41], v108 offset:5120
	ds_read_b128 v[42:45], v108 offset:6144
	ds_read_b128 v[34:37], v108 offset:7168
	v_permlane32_swap_b32_e32 v110, v109
	v_max_f32_e32 v108, v110, v110
	v_max_f32_e32 v108, v109, v108
	v_cmp_gt_f32_e32 vcc, v108, v91
	s_cbranch_vccz .LBB0_656
	v_max_f32_e32 v108, v108, v108
	v_max_f32_e32 v109, v91, v91
	v_max_f32_e32 v109, v109, v108
	v_sub_f32_e32 v91, v91, v109
	v_exp_f32_e32 v108, v91
	v_mov_b32_e32 v91, v109
	v_pk_mul_f32 v[16:17], v[16:17], v[108:109] op_sel_hi:[1,0]
	v_pk_mul_f32 v[14:15], v[14:15], v[108:109] op_sel_hi:[1,0]
	v_pk_mul_f32 v[12:13], v[12:13], v[108:109] op_sel_hi:[1,0]
	v_pk_mul_f32 v[10:11], v[10:11], v[108:109] op_sel_hi:[1,0]
	v_pk_mul_f32 v[8:9], v[8:9], v[108:109] op_sel_hi:[1,0]
	v_pk_mul_f32 v[6:7], v[6:7], v[108:109] op_sel_hi:[1,0]
	v_pk_mul_f32 v[4:5], v[4:5], v[108:109] op_sel_hi:[1,0]
	v_pk_mul_f32 v[2:3], v[2:3], v[108:109] op_sel_hi:[1,0]
	v_pk_mul_f32 v[32:33], v[32:33], v[108:109] op_sel_hi:[1,0]
	v_pk_mul_f32 v[30:31], v[30:31], v[108:109] op_sel_hi:[1,0]
	v_pk_mul_f32 v[28:29], v[28:29], v[108:109] op_sel_hi:[1,0]
	v_pk_mul_f32 v[26:27], v[26:27], v[108:109] op_sel_hi:[1,0]
	v_pk_mul_f32 v[24:25], v[24:25], v[108:109] op_sel_hi:[1,0]
	v_pk_mul_f32 v[22:23], v[22:23], v[108:109] op_sel_hi:[1,0]
	v_pk_mul_f32 v[20:21], v[20:21], v[108:109] op_sel_hi:[1,0]
	v_pk_mul_f32 v[18:19], v[18:19], v[108:109] op_sel_hi:[1,0]
	v_mul_f32_e32 v77, v77, v108
; __device__ __forceinline__ unsigned cvtpk(float lo, float hi) { f32x2_t v = {lo, hi}; bf16x2_t b = __builtin_convertvector(v, bf16x2_t); return __builtin_bit_cast(unsigned, b); }
; template <class BiasF> ...
;     ...
;             float ps = 0.f;
; #pragma unroll
;             for (int r = 0; r < 16; ++r) { sc[r] = __builtin_amdgcn_exp2f(sc[r] - m); ps += sc[r]; asm volatile("" : "+v"(ps)); }
;             l += ps; u32x4 w0, w1;
;             w0.x = cvtpk(sc[0], sc[1]); w0.y = cvtpk(sc[2], sc[3]); w0.z = cvtpk(sc[4], sc[5]); w0.w = cvtpk(sc[6], sc[7]);
;             w1.x = cvtpk(sc[8], sc[9]); w1.y = cvtpk(sc[10], sc[11]); w1.z = cvtpk(sc[12], sc[13]); w1.w = cvtpk(sc[14], sc[15]);
;             const bf16x8 p0 = __builtin_bit_cast(bf16x8, w0), p1 = __builtin_bit_cast(bf16x8, w1);
; #pragma unroll
;             for (int i2 = 0; i2 < 2; ++i2) { o[i2] = __builtin_amdgcn_mfma_f32_32x32x16_bf16(VA[i2][0], p0, o[i2], 0, 0, 0); o[i2] = __builtin_amdgcn_mfma_f32_32x32x16_bf16(VA[i2][1], p1, o[i2], 0, 0, 0); }
.LBB0_656:
	v_sub_f32_e32 v99, v99, v91
	v_exp_f32_e32 v99, v99
	v_sub_f32_e32 v97, v97, v91
	v_exp_f32_e32 v97, v97
	v_sub_f32_e32 v98, v98, v91
	v_add_f32_e32 v108, 0, v99
	v_exp_f32_e32 v98, v98
	v_sub_f32_e32 v95, v95, v91
	v_add_f32_e32 v108, v108, v97
	v_exp_f32_e32 v95, v95
	v_sub_f32_e32 v96, v96, v91
	v_add_f32_e32 v108, v108, v98
	v_exp_f32_e32 v96, v96
	v_sub_f32_e32 v93, v93, v91
	v_add_f32_e32 v108, v95, v108
	v_exp_f32_e32 v109, v93
	v_sub_f32_e32 v93, v94, v91
	v_add_f32_e32 v108, v96, v108
	v_exp_f32_e32 v110, v93
	v_sub_f32_e32 v92, v92, v91
	v_add_f32_e32 v93, v109, v108
	v_exp_f32_e32 v108, v92
	v_sub_f32_e32 v92, v107, v91
	v_exp_f32_e32 v107, v92
	v_add_f32_e32 v93, v110, v93
	v_cvt_pk_bf16_f32 v94, v96, v109
	v_add_f32_e32 v92, v108, v93
	v_cvt_pk_bf16_f32 v93, v98, v95
	v_add_f32_e32 v111, v107, v92
	v_sub_f32_e32 v92, v105, v91
	v_exp_f32_e32 v105, v92
	v_sub_f32_e32 v92, v106, v91
	v_exp_f32_e32 v106, v92
	v_sub_f32_e32 v92, v103, v91
	v_exp_f32_e32 v103, v92
	v_sub_f32_e32 v92, v104, v91
	v_exp_f32_e32 v104, v92
	v_sub_f32_e32 v92, v101, v91
	v_exp_f32_e32 v101, v92
	v_cvt_pk_bf16_f32 v92, v99, v97
	v_cvt_pk_bf16_f32 v95, v110, v108
	v_sub_f32_e32 v102, v102, v91
	v_exp_f32_e32 v96, v102
	s_waitcnt lgkmcnt(0)
	v_mfma_f32_32x32x16_bf16 v[18:33], v[46:49], v[92:95], v[18:33]
	v_sub_f32_e32 v46, v100, v91
	v_exp_f32_e32 v97, v46
	v_cvt_pk_bf16_f32 v46, v107, v105
	v_cvt_pk_bf16_f32 v47, v106, v103
	v_cvt_pk_bf16_f32 v48, v104, v101
	v_cvt_pk_bf16_f32 v49, v96, v97
	v_mfma_f32_32x32x16_bf16 v[2:17], v[38:41], v[92:95], v[2:17]
	s_nop 0
	v_mfma_f32_32x32x16_bf16 v[18:33], v[42:45], v[46:49], v[18:33]
	v_add_f32_e32 v42, v105, v111
	s_nop 0
	v_add_f32_e32 v42, v106, v42
	s_nop 0
	v_add_f32_e32 v42, v103, v42
	v_mfma_f32_32x32x16_bf16 v[2:17], v[34:37], v[46:49], v[2:17]
	v_add_f32_e32 v42, v104, v42
	s_nop 0
	v_add_f32_e32 v38, v101, v42
	s_nop 0
	v_add_f32_e32 v38, v96, v38
	s_nop 0
	v_add_f32_e32 v38, v97, v38
	s_nop 0
	v_add_f32_e32 v77, v77, v38

; __device__ __forceinline__ float shx(float v, int mask, int lane) { return __builtin_bit_cast(float, __builtin_amdgcn_ds_bpermute((lane ^ mask) << 2, __builtin_bit_cast(int, v))); }
; template <class BiasF> ...
;     ...
;             for (int d0 = 0; d0 < 4; ++d0) sc = __builtin_amdgcn_mfma_f32_32x32x16_bf16(KF[d0], qr[d0], sc, 0, 0, 0);
;             const float ktf = (float)(kt + 8 * hi);
;             float tmax = -3.0e38f;
; #pragma unroll
;             for (int r = 0; r < 16; ++r) { sc[r] = sc[r] * c2 + bias.at(r32, kt, ktf + (float)(16 * (r >> 3) + 4 * ((r >> 2) & 1) + (r & 3)), r); tmax = fmaxf(tmax, sc[r]); }
;             tmax = fmaxf(tmax, shx(tmax, 32, lane));
;             if (__any(tmax > m)) { const float mn = fmaxf(m, tmax); const float alpha = __builtin_amdgcn_exp2f(m - mn); m = mn; l *= alpha;
; #pragma unroll
;                 for (int i2 = 0; i2 < 2; ++i2)
; #pragma unroll
;                     for (int r = 0; r < 16; ++r) o[i2][r] *= alpha; }
.LBB0_676:
	s_cmp_lt_i32 s10, s27
	s_cselect_b64 s[6:7], -1, 0
	s_cmp_ge_u32 s10, s28
	s_cselect_b64 s[30:31], -1, 0
	s_or_b64 s[6:7], s[6:7], s[30:31]
	s_and_b64 vcc, exec, s[6:7]
	s_cbranch_vccnz .LBB0_680
	v_lshl_add_u32 v100, s26, 13, v79
	ds_read_b128 v[34:37], v100
	v_add_u32_e32 v38, s10, v66
	v_cvt_f32_i32_e32 v84, v38
	ds_read_b128 v[88:91], v100 offset:1024
	ds_read_b128 v[92:95], v100 offset:2048
	ds_read_b128 v[96:99], v100 offset:3072
	s_waitcnt lgkmcnt(0)
	v_mfma_f32_32x32x16_bf16 v[34:49], v[34:37], v[50:53], 0
	v_sub_f32_e32 v85, v81, v84
	v_add_f32_e32 v86, 1.0, v84
	v_add_f32_e32 v87, 2.0, v84
	v_mul_f32_e64 v102, v82, |v85|
	v_sub_f32_e32 v86, v81, v86
	v_cmp_le_f32_e64 vcc, |v85|, s33
	v_add_f32_e32 v101, 0x40400000, v84
	v_mfma_f32_32x32x16_bf16 v[34:49], v[88:91], v[54:57], v[34:49]
	v_sub_f32_e32 v103, v81, v87
	v_cndmask_b32_e32 v87, v203, v102, vcc
	v_mul_f32_e64 v85, v82, |v86|
	v_cmp_le_f32_e64 vcc, |v86|, s33
	v_sub_f32_e32 v101, v81, v101
	v_mul_f32_e64 v88, v82, |v103|
	v_cndmask_b32_e32 v89, v203, v85, vcc
	v_mfma_f32_32x32x16_bf16 v[34:49], v[92:95], v[58:61], v[34:49]
	v_cmp_le_f32_e64 vcc, |v103|, s33
	v_add_f32_e32 v86, 4.0, v84
	v_mul_f32_e64 v90, v82, |v101|
	v_cndmask_b32_e32 v88, v203, v88, vcc
	v_cmp_le_f32_e64 vcc, |v101|, s33
	v_sub_f32_e32 v86, v81, v86
	v_mfma_f32_32x32x16_bf16 v[34:49], v[96:99], v[62:65], v[34:49]
	v_cndmask_b32_e32 v85, v203, v90, vcc
	v_mul_f32_e64 v90, v82, |v86|
	v_cmp_le_f32_e64 vcc, |v86|, s33
	s_nop 1
	v_cndmask_b32_e32 v86, v203, v90, vcc
	v_add_f32_e32 v90, 0x40a00000, v84
	v_sub_f32_e32 v90, v81, v90
	s_nop 3
	v_fmac_f32_e32 v89, 0x3e38aa3b, v35
	v_add_f32_e32 v35, 0x40c00000, v84
	v_mul_f32_e64 v91, v82, |v90|
	v_cmp_le_f32_e64 vcc, |v90|, s33
	v_sub_f32_e32 v35, v81, v35
	v_fmac_f32_e32 v88, 0x3e38aa3b, v36
	v_cndmask_b32_e32 v90, v203, v91, vcc
	v_mul_f32_e64 v36, v82, |v35|
	v_cmp_le_f32_e64 vcc, |v35|, s33
	v_add_f32_e32 v35, 0x40e00000, v84
	v_sub_f32_e32 v35, v81, v35
	v_cndmask_b32_e32 v92, v203, v36, vcc
	v_mul_f32_e64 v36, v82, |v35|
	v_cmp_le_f32_e64 vcc, |v35|, s33
	v_add_f32_e32 v35, 0x41800000, v84
	v_sub_f32_e32 v35, v81, v35
	v_cndmask_b32_e32 v91, v203, v36, vcc
	v_mul_f32_e64 v36, v82, |v35|
	v_cmp_le_f32_e64 vcc, |v35|, s33
	v_add_f32_e32 v35, 0x41880000, v84
	v_sub_f32_e32 v35, v81, v35
	v_cndmask_b32_e32 v94, v203, v36, vcc
	v_mul_f32_e64 v36, v82, |v35|
	v_cmp_le_f32_e64 vcc, |v35|, s33
	v_add_f32_e32 v35, 0x41900000, v84
	v_sub_f32_e32 v35, v81, v35
	v_cndmask_b32_e32 v93, v203, v36, vcc
	v_mul_f32_e64 v36, v82, |v35|
	v_cmp_le_f32_e64 vcc, |v35|, s33
	v_add_f32_e32 v35, 0x41980000, v84
	v_sub_f32_e32 v35, v81, v35
	v_cndmask_b32_e32 v95, v203, v36, vcc
	v_mul_f32_e64 v36, v82, |v35|
	v_cmp_le_f32_e64 vcc, |v35|, s33
	v_add_f32_e32 v35, 0x41a00000, v84
	v_sub_f32_e32 v35, v81, v35
	v_cndmask_b32_e32 v96, v203, v36, vcc
	v_mul_f32_e64 v36, v82, |v35|
	v_cmp_le_f32_e64 vcc, |v35|, s33
	v_add_f32_e32 v35, 0x41a80000, v84
	v_fmac_f32_e32 v87, 0x3e38aa3b, v34
	v_sub_f32_e32 v35, v81, v35
	v_fmac_f32_e32 v85, 0x3e38aa3b, v37
	v_max3_f32 v34, v87, s53, v89
	v_cndmask_b32_e32 v97, v203, v36, vcc
	v_mul_f32_e64 v36, v82, |v35|
	v_cmp_le_f32_e64 vcc, |v35|, s33
	v_add_f32_e32 v35, 0x41b00000, v84
	v_fmac_f32_e32 v86, 0x3e38aa3b, v38
	v_max3_f32 v34, v34, v88, v85
	v_fmac_f32_e32 v90, 0x3e38aa3b, v39
	v_sub_f32_e32 v35, v81, v35
	v_max3_f32 v34, v34, v86, v90
	v_fmac_f32_e32 v92, 0x3e38aa3b, v40
	v_fmac_f32_e32 v91, 0x3e38aa3b, v41
	v_cndmask_b32_e32 v98, v203, v36, vcc
	v_mul_f32_e64 v36, v82, |v35|
	v_cmp_le_f32_e64 vcc, |v35|, s33
	v_add_f32_e32 v35, 0x41b80000, v84
	v_max3_f32 v34, v34, v92, v91
	v_fmac_f32_e32 v94, 0x3e38aa3b, v42
	v_fmac_f32_e32 v93, 0x3e38aa3b, v43
	v_sub_f32_e32 v35, v81, v35
	v_max3_f32 v34, v34, v94, v93
	v_fmac_f32_e32 v95, 0x3e38aa3b, v44
	v_fmac_f32_e32 v96, 0x3e38aa3b, v45
	v_cndmask_b32_e32 v99, v203, v36, vcc
	v_mul_f32_e64 v36, v82, |v35|
	v_cmp_le_f32_e64 vcc, |v35|, s33
	v_max3_f32 v34, v34, v95, v96
	v_fmac_f32_e32 v97, 0x3e38aa3b, v46
	v_fmac_f32_e32 v98, 0x3e38aa3b, v47
	v_cndmask_b32_e32 v84, v203, v36, vcc
	v_max3_f32 v34, v34, v97, v98
	v_fmac_f32_e32 v99, 0x3e38aa3b, v48
	v_fmac_f32_e32 v84, 0x3e38aa3b, v49
	v_max3_f32 v101, v34, v99, v84
	v_mov_b32_e32 v102, v101
	ds_read_b128 v[46:49], v100 offset:4096
	ds_read_b128 v[38:41], v100 offset:5120
	ds_read_b128 v[42:45], v100 offset:6144
	ds_read_b128 v[34:37], v100 offset:7168
	v_permlane32_swap_b32_e32 v102, v101
	v_max_f32_e32 v100, v102, v102
	v_max_f32_e32 v100, v101, v100
	v_cmp_gt_f32_e32 vcc, v100, v83
	s_cbranch_vccz .LBB0_679
	v_max_f32_e32 v100, v100, v100
	v_max_f32_e32 v101, v83, v83
	v_max_f32_e32 v101, v101, v100
	v_sub_f32_e32 v83, v83, v101
	v_exp_f32_e32 v100, v83
	v_mov_b32_e32 v83, v101
	v_pk_mul_f32 v[16:17], v[16:17], v[100:101] op_sel_hi:[1,0]
	v_pk_mul_f32 v[14:15], v[14:15], v[100:101] op_sel_hi:[1,0]
	v_pk_mul_f32 v[12:13], v[12:13], v[100:101] op_sel_hi:[1,0]
	v_pk_mul_f32 v[10:11], v[10:11], v[100:101] op_sel_hi:[1,0]
	v_pk_mul_f32 v[8:9], v[8:9], v[100:101] op_sel_hi:[1,0]
	v_pk_mul_f32 v[6:7], v[6:7], v[100:101] op_sel_hi:[1,0]
	v_pk_mul_f32 v[4:5], v[4:5], v[100:101] op_sel_hi:[1,0]
	v_pk_mul_f32 v[2:3], v[2:3], v[100:101] op_sel_hi:[1,0]
	v_pk_mul_f32 v[32:33], v[32:33], v[100:101] op_sel_hi:[1,0]
	v_pk_mul_f32 v[30:31], v[30:31], v[100:101] op_sel_hi:[1,0]
	v_pk_mul_f32 v[28:29], v[28:29], v[100:101] op_sel_hi:[1,0]
	v_pk_mul_f32 v[26:27], v[26:27], v[100:101] op_sel_hi:[1,0]
	v_pk_mul_f32 v[24:25], v[24:25], v[100:101] op_sel_hi:[1,0]
	v_pk_mul_f32 v[22:23], v[22:23], v[100:101] op_sel_hi:[1,0]
	v_pk_mul_f32 v[20:21], v[20:21], v[100:101] op_sel_hi:[1,0]
	v_pk_mul_f32 v[18:19], v[18:19], v[100:101] op_sel_hi:[1,0]
	v_mul_f32_e32 v80, v80, v100
; __device__ __forceinline__ unsigned cvtpk(float lo, float hi) { f32x2_t v = {lo, hi}; bf16x2_t b = __builtin_convertvector(v, bf16x2_t); return __builtin_bit_cast(unsigned, b); }
; template <class BiasF> ...
;     ...
;             float ps = 0.f;
; #pragma unroll
;             for (int r = 0; r < 16; ++r) { sc[r] = __builtin_amdgcn_exp2f(sc[r] - m); ps += sc[r]; asm volatile("" : "+v"(ps)); }
;             l += ps; u32x4 w0, w1;
;             w0.x = cvtpk(sc[0], sc[1]); w0.y = cvtpk(sc[2], sc[3]); w0.z = cvtpk(sc[4], sc[5]); w0.w = cvtpk(sc[6], sc[7]);
;             w1.x = cvtpk(sc[8], sc[9]); w1.y = cvtpk(sc[10], sc[11]); w1.z = cvtpk(sc[12], sc[13]); w1.w = cvtpk(sc[14], sc[15]);
;             const bf16x8 p0 = __builtin_bit_cast(bf16x8, w0), p1 = __builtin_bit_cast(bf16x8, w1);
; #pragma unroll
;             for (int i2 = 0; i2 < 2; ++i2) { o[i2] = __builtin_amdgcn_mfma_f32_32x32x16_bf16(VA[i2][0], p0, o[i2], 0, 0, 0); o[i2] = __builtin_amdgcn_mfma_f32_32x32x16_bf16(VA[i2][1], p1, o[i2], 0, 0, 0); }
.LBB0_679:
	v_sub_f32_e32 v87, v87, v83
	v_exp_f32_e32 v87, v87
	v_sub_f32_e32 v89, v89, v83
	v_exp_f32_e32 v89, v89
	v_sub_f32_e32 v88, v88, v83
	v_add_f32_e32 v100, 0, v87
	v_exp_f32_e32 v88, v88
	v_sub_f32_e32 v85, v85, v83
	v_exp_f32_e32 v85, v85
	v_add_f32_e32 v100, v100, v89
	v_sub_f32_e32 v86, v86, v83
	v_exp_f32_e32 v101, v86
	v_add_f32_e32 v100, v100, v88
	v_sub_f32_e32 v90, v90, v83
	v_exp_f32_e32 v90, v90
	v_add_f32_e32 v86, v85, v100
	v_sub_f32_e32 v92, v92, v83
	v_add_f32_e32 v86, v101, v86
	v_exp_f32_e32 v92, v92
	v_sub_f32_e32 v91, v91, v83
	v_add_f32_e32 v86, v90, v86
	v_exp_f32_e32 v91, v91
	v_sub_f32_e32 v94, v94, v83
	v_add_f32_e32 v86, v92, v86
	v_exp_f32_e32 v94, v94
	v_sub_f32_e32 v99, v99, v83
	v_add_f32_e32 v86, v91, v86
	s_nop 0
	v_add_f32_e32 v100, v94, v86
	v_sub_f32_e32 v86, v93, v83
	v_exp_f32_e32 v93, v86
	v_sub_f32_e32 v86, v95, v83
	v_exp_f32_e32 v95, v86
	v_sub_f32_e32 v86, v96, v83
	v_exp_f32_e32 v96, v86
	v_sub_f32_e32 v86, v97, v83
	v_exp_f32_e32 v97, v86
	v_sub_f32_e32 v86, v98, v83
	v_exp_f32_e32 v98, v86
	v_cvt_pk_bf16_f32 v86, v87, v89
	v_cvt_pk_bf16_f32 v87, v88, v85
	v_cvt_pk_bf16_f32 v88, v101, v90
	v_cvt_pk_bf16_f32 v89, v92, v91
	v_exp_f32_e32 v85, v99
	s_nop 0
	s_waitcnt lgkmcnt(0)
	v_mfma_f32_32x32x16_bf16 v[18:33], v[46:49], v[86:89], v[18:33]
	v_sub_f32_e32 v46, v84, v83
	v_exp_f32_e32 v84, v46
	v_cvt_pk_bf16_f32 v46, v94, v93
	v_cvt_pk_bf16_f32 v47, v95, v96
	v_cvt_pk_bf16_f32 v48, v97, v98
	v_cvt_pk_bf16_f32 v49, v85, v84
	v_mfma_f32_32x32x16_bf16 v[2:17], v[38:41], v[86:89], v[2:17]
	s_nop 0
	v_mfma_f32_32x32x16_bf16 v[18:33], v[42:45], v[46:49], v[18:33]
	v_add_f32_e32 v42, v93, v100
	s_nop 0
	v_add_f32_e32 v42, v95, v42
	s_nop 0
	v_add_f32_e32 v42, v96, v42
	v_mfma_f32_32x32x16_bf16 v[2:17], v[34:37], v[46:49], v[2:17]
	v_add_f32_e32 v42, v97, v42
	s_nop 0
	v_add_f32_e32 v38, v98, v42
	s_nop 0
	v_add_f32_e32 v38, v85, v38
	s_nop 0
	v_add_f32_e32 v38, v84, v38
	s_nop 0
	v_add_f32_e32 v80, v80, v38
